# GEMM tile headers: 128 v_mov_b32 accumulator clears replaced by 64 v_mov_b64
# speedup vs baseline: 1.0085x; 1.0037x over previous
; template <class Epi, class Sched, bool ALIGN_EPI = false, bool SP2 = false>
; __device__ __forceinline__ void gemm_phase(PG8_LAS unsigned char* lds, const Gemm g, const Sched& S, const Epi& E) {
;     ...
;         const bool has_next = S.next(ui + 1, nxt);
;         const char* nA = has_next ? (const char*)g.A + (size_t)nxt.pm * tstep : cA; const char* nB = has_next ? (const char*)g.Bt + (size_t)nxt.pn * tstep : cB;
;     ...
;         for (int a = 0; a < 2; ++a)
; #pragma unroll
;             for (int b = 0; b < 2; ++b)
; #pragma unroll
;                 for (int m = 0; m < 4; ++m)
; #pragma unroll
;                     for (int n = 0; n < 2; ++n) acc[a][b][m][n] = (f32x4){0.f, 0.f, 0.f, 0.f};
.LBB0_340:
	s_ashr_i32 s69, s68, 31
	s_lshl_b64 s[0:1], s[68:69], 20
	s_add_u32 s72, s17, s0
	s_addc_u32 s73, s19, s1
	s_and_b64 s[0:1], s[4:5], exec
	s_cselect_b32 s7, s73, s11
	s_cselect_b32 s9, s72, s10
	s_ashr_i32 s71, s70, 31
	s_lshl_b64 s[0:1], s[70:71], 20
	s_add_u32 s0, s28, s0
	s_addc_u32 s1, s29, s1
	s_and_b64 s[46:47], s[4:5], exec
	s_cselect_b32 s12, s1, s15
	s_cselect_b32 s45, s0, s14
	s_add_u32 s10, s10, 0x80080
	s_addc_u32 s11, s11, 0
	s_add_u32 s46, s14, 0x100
	v_mov_b64_e32 v[0:1], 0
	s_addc_u32 s47, s15, 0
	s_mov_b32 s48, -2
	s_waitcnt lgkmcnt(0)
	v_mov_b64_e32 v[2:3], 0
	v_mov_b64_e32 v[4:5], 0
	v_mov_b64_e32 v[6:7], 0
	v_mov_b64_e32 v[16:17], 0
	v_mov_b64_e32 v[18:19], 0
	v_mov_b64_e32 v[20:21], 0
	v_mov_b64_e32 v[22:23], 0
	v_mov_b64_e32 v[32:33], 0
	v_mov_b64_e32 v[34:35], 0
	v_mov_b64_e32 v[36:37], 0
	v_mov_b64_e32 v[38:39], 0
	v_mov_b64_e32 v[48:49], 0
	v_mov_b64_e32 v[50:51], 0
	v_mov_b64_e32 v[52:53], 0
	v_mov_b64_e32 v[54:55], 0
	v_mov_b64_e32 v[8:9], 0
	v_mov_b64_e32 v[10:11], 0
	v_mov_b64_e32 v[12:13], 0
	v_mov_b64_e32 v[14:15], 0
	v_mov_b64_e32 v[24:25], 0
	v_mov_b64_e32 v[26:27], 0
	v_mov_b64_e32 v[28:29], 0
	v_mov_b64_e32 v[30:31], 0
	v_mov_b64_e32 v[40:41], 0
	v_mov_b64_e32 v[42:43], 0
	v_mov_b64_e32 v[44:45], 0
	v_mov_b64_e32 v[46:47], 0
	v_mov_b64_e32 v[56:57], 0
	v_mov_b64_e32 v[58:59], 0
	v_mov_b64_e32 v[60:61], 0
	v_mov_b64_e32 v[62:63], 0
	v_mov_b64_e32 v[64:65], 0
	v_mov_b64_e32 v[66:67], 0
	v_mov_b64_e32 v[68:69], 0
	v_mov_b64_e32 v[70:71], 0
	v_mov_b64_e32 v[80:81], 0
	v_mov_b64_e32 v[82:83], 0
	v_mov_b64_e32 v[84:85], 0
	v_mov_b64_e32 v[86:87], 0
	v_mov_b64_e32 v[96:97], 0
	v_mov_b64_e32 v[98:99], 0
	v_mov_b64_e32 v[100:101], 0
	v_mov_b64_e32 v[102:103], 0
	v_mov_b64_e32 v[112:113], 0
	v_mov_b64_e32 v[114:115], 0
	v_mov_b64_e32 v[116:117], 0
	v_mov_b64_e32 v[118:119], 0
	v_mov_b64_e32 v[72:73], 0
	v_mov_b64_e32 v[74:75], 0
	v_mov_b64_e32 v[76:77], 0
	v_mov_b64_e32 v[78:79], 0
	v_mov_b64_e32 v[88:89], 0
	v_mov_b64_e32 v[90:91], 0
	v_mov_b64_e32 v[92:93], 0
	v_mov_b64_e32 v[94:95], 0
	v_mov_b64_e32 v[104:105], 0
	v_mov_b64_e32 v[106:107], 0
	v_mov_b64_e32 v[108:109], 0
	v_mov_b64_e32 v[110:111], 0
	v_mov_b64_e32 v[120:121], 0
	v_mov_b64_e32 v[122:123], 0
	v_mov_b64_e32 v[124:125], 0
	v_mov_b64_e32 v[126:127], 0

; template <class Epi, class Sched, bool ALIGN_EPI = false, bool SP2 = false>
; __device__ __forceinline__ void gemm_phase(PG8_LAS unsigned char* lds, const Gemm g, const Sched& S, const Epi& E) {
;     ...
;         for (int a = 0; a < 2; ++a)
; #pragma unroll
;             for (int b = 0; b < 2; ++b)
; #pragma unroll
;                 for (int m = 0; m < 4; ++m)
; #pragma unroll
;                     for (int n = 0; n < 2; ++n) acc[a][b][m][n] = (f32x4){0.f, 0.f, 0.f, 0.f};
.LBB0_917:
	v_mov_b32_e32 v123, 0
	s_andn2_b64 vcc, exec, s[66:67]
	v_mov_b32_e32 v122, v123
	v_mov_b32_e32 v121, v123
	v_mov_b32_e32 v120, v123
	v_mov_b32_e32 v127, v123
	v_mov_b32_e32 v126, v123
	v_mov_b32_e32 v125, v123
	v_mov_b32_e32 v124, v123
	v_mov_b32_e32 v111, v123
	v_mov_b32_e32 v110, v123
	v_mov_b32_e32 v109, v123
	v_mov_b32_e32 v108, v123
	v_mov_b32_e32 v107, v123
	v_mov_b32_e32 v106, v123
	v_mov_b32_e32 v105, v123
	v_mov_b32_e32 v104, v123
	v_mov_b32_e32 v95, v123
	v_mov_b32_e32 v94, v123
	v_mov_b32_e32 v93, v123
	v_mov_b32_e32 v92, v123
	v_mov_b32_e32 v91, v123
	v_mov_b32_e32 v90, v123
	v_mov_b32_e32 v89, v123
	v_mov_b32_e32 v88, v123
	v_mov_b32_e32 v79, v123
	v_mov_b32_e32 v78, v123
	v_mov_b32_e32 v77, v123
	v_mov_b32_e32 v76, v123
	v_mov_b32_e32 v75, v123
	v_mov_b32_e32 v74, v123
	v_mov_b32_e32 v73, v123
	v_mov_b32_e32 v72, v123
	v_mov_b32_e32 v119, v123
	v_mov_b32_e32 v118, v123
	v_mov_b32_e32 v117, v123
	v_mov_b32_e32 v116, v123
	v_mov_b32_e32 v115, v123
	v_mov_b32_e32 v114, v123
	v_mov_b32_e32 v113, v123
	v_mov_b32_e32 v112, v123
	v_mov_b32_e32 v103, v123
	v_mov_b32_e32 v102, v123
	v_mov_b32_e32 v101, v123
	v_mov_b32_e32 v100, v123
	v_mov_b32_e32 v99, v123
	v_mov_b32_e32 v98, v123
	v_mov_b32_e32 v97, v123
	v_mov_b32_e32 v96, v123
	v_mov_b32_e32 v87, v123
	v_mov_b32_e32 v86, v123
	v_mov_b32_e32 v85, v123
	v_mov_b32_e32 v84, v123
	v_mov_b32_e32 v83, v123
	v_mov_b32_e32 v82, v123
	v_mov_b32_e32 v81, v123
	v_mov_b32_e32 v80, v123
	v_mov_b32_e32 v71, v123
	v_mov_b32_e32 v70, v123
	v_mov_b32_e32 v69, v123
	v_mov_b32_e32 v68, v123
	v_mov_b32_e32 v67, v123
	v_mov_b32_e32 v66, v123
	v_mov_b32_e32 v65, v123
	v_mov_b32_e32 v64, v123
	v_mov_b32_e32 v63, v123
	v_mov_b32_e32 v62, v123
	v_mov_b32_e32 v61, v123
	v_mov_b32_e32 v60, v123
	v_mov_b32_e32 v59, v123
	v_mov_b32_e32 v58, v123
	v_mov_b32_e32 v57, v123
	v_mov_b32_e32 v56, v123
	v_mov_b32_e32 v47, v123
	v_mov_b32_e32 v46, v123
	v_mov_b32_e32 v45, v123
	v_mov_b32_e32 v44, v123
	v_mov_b32_e32 v43, v123
	v_mov_b32_e32 v42, v123
	v_mov_b32_e32 v41, v123
	v_mov_b32_e32 v40, v123
	v_mov_b32_e32 v31, v123
	v_mov_b32_e32 v30, v123
	v_mov_b32_e32 v29, v123
	v_mov_b32_e32 v28, v123
	v_mov_b32_e32 v27, v123
	v_mov_b32_e32 v26, v123
	v_mov_b32_e32 v25, v123
	v_mov_b32_e32 v24, v123
	v_mov_b32_e32 v15, v123
	v_mov_b32_e32 v14, v123
	v_mov_b32_e32 v13, v123
	v_mov_b32_e32 v12, v123
	v_mov_b32_e32 v11, v123
	v_mov_b32_e32 v10, v123
	v_mov_b32_e32 v9, v123
	v_mov_b32_e32 v8, v123
	v_mov_b32_e32 v55, v123
	v_mov_b32_e32 v54, v123
	v_mov_b32_e32 v53, v123
	v_mov_b32_e32 v52, v123
	v_mov_b32_e32 v51, v123
	v_mov_b32_e32 v50, v123
	v_mov_b32_e32 v49, v123
	v_mov_b32_e32 v48, v123
	v_mov_b32_e32 v39, v123
	v_mov_b32_e32 v38, v123
	v_mov_b32_e32 v37, v123
	v_mov_b32_e32 v36, v123
	v_mov_b32_e32 v35, v123
	v_mov_b32_e32 v34, v123
	v_mov_b32_e32 v33, v123
	v_mov_b32_e32 v32, v123
	v_mov_b32_e32 v23, v123
	v_mov_b32_e32 v22, v123
	v_mov_b32_e32 v21, v123
	v_mov_b32_e32 v20, v123
	v_mov_b32_e32 v19, v123
	v_mov_b32_e32 v18, v123
	v_mov_b32_e32 v17, v123
	v_mov_b32_e32 v16, v123
	v_mov_b32_e32 v7, v123
	v_mov_b32_e32 v6, v123
	v_mov_b32_e32 v5, v123
	v_mov_b32_e32 v4, v123
	v_mov_b32_e32 v3, v123
	v_mov_b32_e32 v2, v123
	v_mov_b32_e32 v1, v123
	v_mov_b32_e32 v0, v123
	s_cbranch_vccnz .LBB0_920
	s_add_u32 s0, s0, 0x80
	s_addc_u32 s1, s1, 0
	s_add_u32 s44, s72, 0x100
	v_mov_b64_e32 v[0:1], 0
	s_addc_u32 s45, s73, 0
	s_mov_b32 s6, 0
	v_mov_b64_e32 v[2:3], 0
	v_mov_b64_e32 v[4:5], 0
	v_mov_b64_e32 v[6:7], 0
	v_mov_b64_e32 v[16:17], 0
	v_mov_b64_e32 v[18:19], 0
	v_mov_b64_e32 v[20:21], 0
	v_mov_b64_e32 v[22:23], 0
	v_mov_b64_e32 v[32:33], 0
	v_mov_b64_e32 v[34:35], 0
	v_mov_b64_e32 v[36:37], 0
	v_mov_b64_e32 v[38:39], 0
	v_mov_b64_e32 v[48:49], 0
	v_mov_b64_e32 v[50:51], 0
	v_mov_b64_e32 v[52:53], 0
	v_mov_b64_e32 v[54:55], 0
	v_mov_b64_e32 v[8:9], 0
	v_mov_b64_e32 v[10:11], 0
	v_mov_b64_e32 v[12:13], 0
	v_mov_b64_e32 v[14:15], 0
	v_mov_b64_e32 v[24:25], 0
	v_mov_b64_e32 v[26:27], 0
	v_mov_b64_e32 v[28:29], 0
	v_mov_b64_e32 v[30:31], 0
	v_mov_b64_e32 v[40:41], 0
	v_mov_b64_e32 v[42:43], 0
	v_mov_b64_e32 v[44:45], 0
	v_mov_b64_e32 v[46:47], 0
	v_mov_b64_e32 v[56:57], 0
	v_mov_b64_e32 v[58:59], 0
	v_mov_b64_e32 v[60:61], 0
	v_mov_b64_e32 v[62:63], 0
	v_mov_b64_e32 v[64:65], 0
	v_mov_b64_e32 v[66:67], 0
	v_mov_b64_e32 v[68:69], 0
	v_mov_b64_e32 v[70:71], 0
	v_mov_b64_e32 v[80:81], 0
	v_mov_b64_e32 v[82:83], 0
	v_mov_b64_e32 v[84:85], 0
	v_mov_b64_e32 v[86:87], 0
	v_mov_b64_e32 v[96:97], 0
	v_mov_b64_e32 v[98:99], 0
	v_mov_b64_e32 v[100:101], 0
	v_mov_b64_e32 v[102:103], 0
	v_mov_b64_e32 v[112:113], 0
	v_mov_b64_e32 v[114:115], 0
	v_mov_b64_e32 v[116:117], 0
	v_mov_b64_e32 v[118:119], 0
	v_mov_b64_e32 v[72:73], 0
	v_mov_b64_e32 v[74:75], 0
	v_mov_b64_e32 v[76:77], 0
	v_mov_b64_e32 v[78:79], 0
	v_mov_b64_e32 v[88:89], 0
	v_mov_b64_e32 v[90:91], 0
	v_mov_b64_e32 v[92:93], 0
	v_mov_b64_e32 v[94:95], 0
	v_mov_b64_e32 v[104:105], 0
	v_mov_b64_e32 v[106:107], 0
	v_mov_b64_e32 v[108:109], 0
	v_mov_b64_e32 v[110:111], 0
	v_mov_b64_e32 v[124:125], 0
	v_mov_b64_e32 v[126:127], 0
	v_mov_b64_e32 v[120:121], 0
	v_mov_b64_e32 v[122:123], 0

; template <class Epi, class Sched, bool ALIGN_EPI = false, bool SP2 = false>
; __device__ __forceinline__ void gemm_phase(PG8_LAS unsigned char* lds, const Gemm g, const Sched& S, const Epi& E) {
;     ...
;         const bool has_next = S.next(ui + 1, nxt);
;         const char* nA = has_next ? (const char*)g.A + (size_t)nxt.pm * tstep : cA; const char* nB = has_next ? (const char*)g.Bt + (size_t)nxt.pn * tstep : cB;
;     ...
;         for (int a = 0; a < 2; ++a)
; #pragma unroll
;             for (int b = 0; b < 2; ++b)
; #pragma unroll
;                 for (int m = 0; m < 4; ++m)
; #pragma unroll
;                     for (int n = 0; n < 2; ++n) acc[a][b][m][n] = (f32x4){0.f, 0.f, 0.f, 0.f};
.LBB0_1439:
	s_ashr_i32 s47, s46, 31
	s_lshl_b64 s[48:49], s[46:47], 20
	s_add_u32 s48, s60, s48
	s_addc_u32 s49, s61, s49
	s_and_b64 s[52:53], s[4:5], exec
	s_cselect_b32 s47, s49, s55
	s_cselect_b32 s83, s48, s54
	s_ashr_i32 s45, s44, 31
	s_lshl_b64 s[52:53], s[44:45], 20
	s_add_u32 s52, s62, s52
	s_addc_u32 s53, s63, s53
	s_and_b64 s[58:59], s[4:5], exec
	s_cselect_b32 s45, s53, s57
	s_cselect_b32 s84, s52, s56
	s_add_u32 s54, s54, 0x80080
	s_addc_u32 s55, s55, 0
	s_add_u32 s85, s56, 0x100
	v_mov_b64_e32 v[0:1], 0
	s_addc_u32 s86, s57, 0
	s_mov_b32 s87, -2
	v_mov_b64_e32 v[2:3], 0
	v_mov_b64_e32 v[4:5], 0
	v_mov_b64_e32 v[6:7], 0
	v_mov_b64_e32 v[16:17], 0
	v_mov_b64_e32 v[18:19], 0
	v_mov_b64_e32 v[20:21], 0
	v_mov_b64_e32 v[22:23], 0
	v_mov_b64_e32 v[32:33], 0
	v_mov_b64_e32 v[34:35], 0
	v_mov_b64_e32 v[36:37], 0
	v_mov_b64_e32 v[38:39], 0
	v_mov_b64_e32 v[48:49], 0
	v_mov_b64_e32 v[50:51], 0
	v_mov_b64_e32 v[52:53], 0
	v_mov_b64_e32 v[54:55], 0
	v_mov_b64_e32 v[8:9], 0
	v_mov_b64_e32 v[10:11], 0
	v_mov_b64_e32 v[12:13], 0
	v_mov_b64_e32 v[14:15], 0
	v_mov_b64_e32 v[24:25], 0
	v_mov_b64_e32 v[26:27], 0
	v_mov_b64_e32 v[28:29], 0
	v_mov_b64_e32 v[30:31], 0
	v_mov_b64_e32 v[40:41], 0
	v_mov_b64_e32 v[42:43], 0
	v_mov_b64_e32 v[44:45], 0
	v_mov_b64_e32 v[46:47], 0
	v_mov_b64_e32 v[56:57], 0
	v_mov_b64_e32 v[58:59], 0
	v_mov_b64_e32 v[60:61], 0
	v_mov_b64_e32 v[62:63], 0
	v_mov_b64_e32 v[64:65], 0
	v_mov_b64_e32 v[66:67], 0
	v_mov_b64_e32 v[68:69], 0
	v_mov_b64_e32 v[70:71], 0
	v_mov_b64_e32 v[80:81], 0
	v_mov_b64_e32 v[82:83], 0
	v_mov_b64_e32 v[84:85], 0
	v_mov_b64_e32 v[86:87], 0
	v_mov_b64_e32 v[96:97], 0
	v_mov_b64_e32 v[98:99], 0
	v_mov_b64_e32 v[100:101], 0
	v_mov_b64_e32 v[102:103], 0
	v_mov_b64_e32 v[112:113], 0
	v_mov_b64_e32 v[114:115], 0
	v_mov_b64_e32 v[116:117], 0
	v_mov_b64_e32 v[118:119], 0
	v_mov_b64_e32 v[72:73], 0
	v_mov_b64_e32 v[74:75], 0
	v_mov_b64_e32 v[76:77], 0
	v_mov_b64_e32 v[78:79], 0
	v_mov_b64_e32 v[88:89], 0
	v_mov_b64_e32 v[90:91], 0
	v_mov_b64_e32 v[92:93], 0
	v_mov_b64_e32 v[94:95], 0
	v_mov_b64_e32 v[104:105], 0
	v_mov_b64_e32 v[106:107], 0
	v_mov_b64_e32 v[108:109], 0
	v_mov_b64_e32 v[110:111], 0
	v_mov_b64_e32 v[120:121], 0
	v_mov_b64_e32 v[122:123], 0
	v_mov_b64_e32 v[124:125], 0
	v_mov_b64_e32 v[126:127], 0

; template <class Epi, class Sched, bool ALIGN_EPI = false, bool SP2 = false>
; __device__ __forceinline__ void gemm_phase(PG8_LAS unsigned char* lds, const Gemm g, const Sched& S, const Epi& E) {
;     ...
;         const bool has_next = S.next(ui + 1, nxt);
;         const char* nA = has_next ? (const char*)g.A + (size_t)nxt.pm * tstep : cA; const char* nB = has_next ? (const char*)g.Bt + (size_t)nxt.pn * tstep : cB;
;     ...
;         for (int a = 0; a < 2; ++a)
; #pragma unroll
;             for (int b = 0; b < 2; ++b)
; #pragma unroll
;                 for (int m = 0; m < 4; ++m)
; #pragma unroll
;                     for (int n = 0; n < 2; ++n) acc[a][b][m][n] = (f32x4){0.f, 0.f, 0.f, 0.f};
.LBB0_1459:
	s_ashr_i32 s47, s46, 31
	s_lshl_b64 s[48:49], s[46:47], 19
	s_add_u32 s48, s61, s48
	s_addc_u32 s49, s62, s49
	s_and_b64 s[52:53], s[4:5], exec
	s_cselect_b32 s47, s49, s55
	s_cselect_b32 s81, s48, s54
	s_ashr_i32 s45, s44, 31
	s_lshl_b64 s[52:53], s[44:45], 19
	s_add_u32 s52, s63, s52
	s_addc_u32 s53, s64, s53
	s_and_b64 s[58:59], s[4:5], exec
	s_cselect_b32 s45, s53, s57
	s_cselect_b32 s82, s52, s56
	s_add_u32 s54, s54, 0x40080
	s_addc_u32 s55, s55, 0
	s_add_u32 s83, s56, 0x100
	v_mov_b64_e32 v[0:1], 0
	s_addc_u32 s84, s57, 0
	s_mov_b32 s85, -2
	v_mov_b64_e32 v[2:3], 0
	v_mov_b64_e32 v[4:5], 0
	v_mov_b64_e32 v[6:7], 0
	v_mov_b64_e32 v[8:9], 0
	v_mov_b64_e32 v[10:11], 0
	v_mov_b64_e32 v[12:13], 0
	v_mov_b64_e32 v[14:15], 0
	v_mov_b64_e32 v[24:25], 0
	v_mov_b64_e32 v[26:27], 0
	v_mov_b64_e32 v[28:29], 0
	v_mov_b64_e32 v[30:31], 0
	v_mov_b64_e32 v[40:41], 0
	v_mov_b64_e32 v[42:43], 0
	v_mov_b64_e32 v[44:45], 0
	v_mov_b64_e32 v[46:47], 0
	v_mov_b64_e32 v[16:17], 0
	v_mov_b64_e32 v[18:19], 0
	v_mov_b64_e32 v[20:21], 0
	v_mov_b64_e32 v[22:23], 0
	v_mov_b64_e32 v[32:33], 0
	v_mov_b64_e32 v[34:35], 0
	v_mov_b64_e32 v[36:37], 0
	v_mov_b64_e32 v[38:39], 0
	v_mov_b64_e32 v[48:49], 0
	v_mov_b64_e32 v[50:51], 0
	v_mov_b64_e32 v[52:53], 0
	v_mov_b64_e32 v[54:55], 0
	v_mov_b64_e32 v[56:57], 0
	v_mov_b64_e32 v[58:59], 0
	v_mov_b64_e32 v[60:61], 0
	v_mov_b64_e32 v[62:63], 0
	v_mov_b64_e32 v[64:65], 0
	v_mov_b64_e32 v[66:67], 0
	v_mov_b64_e32 v[68:69], 0
	v_mov_b64_e32 v[70:71], 0
	v_mov_b64_e32 v[72:73], 0
	v_mov_b64_e32 v[74:75], 0
	v_mov_b64_e32 v[76:77], 0
	v_mov_b64_e32 v[78:79], 0
	v_mov_b64_e32 v[88:89], 0
	v_mov_b64_e32 v[90:91], 0
	v_mov_b64_e32 v[92:93], 0
	v_mov_b64_e32 v[94:95], 0
	v_mov_b64_e32 v[104:105], 0
	v_mov_b64_e32 v[106:107], 0
	v_mov_b64_e32 v[108:109], 0
	v_mov_b64_e32 v[110:111], 0
	v_mov_b64_e32 v[80:81], 0
	v_mov_b64_e32 v[82:83], 0
	v_mov_b64_e32 v[84:85], 0
	v_mov_b64_e32 v[86:87], 0
	v_mov_b64_e32 v[96:97], 0
	v_mov_b64_e32 v[98:99], 0
	v_mov_b64_e32 v[100:101], 0
	v_mov_b64_e32 v[102:103], 0
	v_mov_b64_e32 v[112:113], 0
	v_mov_b64_e32 v[114:115], 0
	v_mov_b64_e32 v[116:117], 0
	v_mov_b64_e32 v[118:119], 0
	v_mov_b64_e32 v[120:121], 0
	v_mov_b64_e32 v[122:123], 0
	v_mov_b64_e32 v[124:125], 0
	v_mov_b64_e32 v[126:127], 0

; template <class Epi, class Sched, bool ALIGN_EPI = false, bool SP2 = false>
; __device__ __forceinline__ void gemm_phase(PG8_LAS unsigned char* lds, const Gemm g, const Sched& S, const Epi& E) {
;     ...
;         const bool has_next = S.next(ui + 1, nxt);
;         const char* nA = has_next ? (const char*)g.A + (size_t)nxt.pm * tstep : cA; const char* nB = has_next ? (const char*)g.Bt + (size_t)nxt.pn * tstep : cB;
;     ...
;         for (int a = 0; a < 2; ++a)
; #pragma unroll
;             for (int b = 0; b < 2; ++b)
; #pragma unroll
;                 for (int m = 0; m < 4; ++m)
; #pragma unroll
;                     for (int n = 0; n < 2; ++n) acc[a][b][m][n] = (f32x4){0.f, 0.f, 0.f, 0.f};
.LBB0_1534:
	s_ashr_i32 s23, s22, 31
	s_lshl_b64 s[36:37], s[22:23], 19
	s_add_u32 s36, s3, s36
	s_addc_u32 s37, s33, s37
	s_and_b64 s[38:39], s[4:5], exec
	s_cselect_b32 s23, s37, s43
	s_cselect_b32 s66, s36, s42
	s_ashr_i32 s19, s18, 31
	s_lshl_b64 s[38:39], s[18:19], 19
	s_add_u32 s38, s48, s38
	s_addc_u32 s39, s49, s39
	s_and_b64 s[46:47], s[4:5], exec
	s_cselect_b32 s19, s39, s45
	s_cselect_b32 s67, s38, s44
	s_add_u32 s42, s42, 0x40080
	s_addc_u32 s43, s43, 0
	s_add_u32 s68, s44, 0x100
	v_mov_b64_e32 v[0:1], 0
	s_addc_u32 s69, s45, 0
	s_mov_b32 s70, -2
	v_mov_b64_e32 v[2:3], 0
	v_mov_b64_e32 v[4:5], 0
	v_mov_b64_e32 v[6:7], 0
	v_mov_b64_e32 v[16:17], 0
	v_mov_b64_e32 v[18:19], 0
	v_mov_b64_e32 v[20:21], 0
	v_mov_b64_e32 v[22:23], 0
	v_mov_b64_e32 v[32:33], 0
	v_mov_b64_e32 v[34:35], 0
	v_mov_b64_e32 v[36:37], 0
	v_mov_b64_e32 v[38:39], 0
	v_mov_b64_e32 v[48:49], 0
	v_mov_b64_e32 v[50:51], 0
	v_mov_b64_e32 v[52:53], 0
	v_mov_b64_e32 v[54:55], 0
	v_mov_b64_e32 v[8:9], 0
	v_mov_b64_e32 v[10:11], 0
	v_mov_b64_e32 v[12:13], 0
	v_mov_b64_e32 v[14:15], 0
	v_mov_b64_e32 v[24:25], 0
	v_mov_b64_e32 v[26:27], 0
	v_mov_b64_e32 v[28:29], 0
	v_mov_b64_e32 v[30:31], 0
	v_mov_b64_e32 v[40:41], 0
	v_mov_b64_e32 v[42:43], 0
	v_mov_b64_e32 v[44:45], 0
	v_mov_b64_e32 v[46:47], 0
	v_mov_b64_e32 v[56:57], 0
	v_mov_b64_e32 v[58:59], 0
	v_mov_b64_e32 v[60:61], 0
	v_mov_b64_e32 v[62:63], 0
	v_mov_b64_e32 v[64:65], 0
	v_mov_b64_e32 v[66:67], 0
	v_mov_b64_e32 v[68:69], 0
	v_mov_b64_e32 v[70:71], 0
	v_mov_b64_e32 v[80:81], 0
	v_mov_b64_e32 v[82:83], 0
	v_mov_b64_e32 v[84:85], 0
	v_mov_b64_e32 v[86:87], 0
	v_mov_b64_e32 v[96:97], 0
	v_mov_b64_e32 v[98:99], 0
	v_mov_b64_e32 v[100:101], 0
	v_mov_b64_e32 v[102:103], 0
	v_mov_b64_e32 v[112:113], 0
	v_mov_b64_e32 v[114:115], 0
	v_mov_b64_e32 v[116:117], 0
	v_mov_b64_e32 v[118:119], 0
	v_mov_b64_e32 v[72:73], 0
	v_mov_b64_e32 v[74:75], 0
	v_mov_b64_e32 v[76:77], 0
	v_mov_b64_e32 v[78:79], 0
	v_mov_b64_e32 v[88:89], 0
	v_mov_b64_e32 v[90:91], 0
	v_mov_b64_e32 v[92:93], 0
	v_mov_b64_e32 v[94:95], 0
	v_mov_b64_e32 v[104:105], 0
	v_mov_b64_e32 v[106:107], 0
	v_mov_b64_e32 v[108:109], 0
	v_mov_b64_e32 v[110:111], 0
	v_mov_b64_e32 v[120:121], 0
	v_mov_b64_e32 v[122:123], 0
	v_mov_b64_e32 v[124:125], 0
	v_mov_b64_e32 v[126:127], 0

; template <class Epi, class Sched, bool ALIGN_EPI = false, bool SP2 = false>
; __device__ __forceinline__ void gemm_phase(PG8_LAS unsigned char* lds, const Gemm g, const Sched& S, const Epi& E) {
;     ...
;         const bool has_next = S.next(ui + 1, nxt);
;         const char* nA = has_next ? (const char*)g.A + (size_t)nxt.pm * tstep : cA; const char* nB = has_next ? (const char*)g.Bt + (size_t)nxt.pn * tstep : cB;
;     ...
;         for (int a = 0; a < 2; ++a)
; #pragma unroll
;             for (int b = 0; b < 2; ++b)
; #pragma unroll
;                 for (int m = 0; m < 4; ++m)
; #pragma unroll
;                     for (int n = 0; n < 2; ++n) acc[a][b][m][n] = (f32x4){0.f, 0.f, 0.f, 0.f};
.LBB0_1611:
	s_ashr_i32 s23, s22, 31
	s_lshl_b64 s[36:37], s[22:23], 20
	s_add_u32 s36, s3, s36
	s_addc_u32 s37, s33, s37
	s_and_b64 s[38:39], s[4:5], exec
	s_cselect_b32 s23, s37, s43
	s_cselect_b32 s41, s36, s42
	s_ashr_i32 s19, s18, 31
	s_lshl_b64 s[38:39], s[18:19], 20
	s_add_u32 s38, s48, s38
	s_addc_u32 s39, s49, s39
	s_and_b64 s[46:47], s[4:5], exec
	s_cselect_b32 s19, s39, s45
	s_cselect_b32 s66, s38, s44
	s_add_u32 s42, s42, 0x80080
	s_addc_u32 s43, s43, 0
	s_add_u32 s67, s44, 0x100
	v_mov_b64_e32 v[0:1], 0
	s_addc_u32 s68, s45, 0
	s_mov_b32 s69, -2
	s_waitcnt lgkmcnt(0)
	v_mov_b64_e32 v[2:3], 0
	v_mov_b64_e32 v[4:5], 0
	v_mov_b64_e32 v[6:7], 0
	v_mov_b64_e32 v[16:17], 0
	v_mov_b64_e32 v[18:19], 0
	v_mov_b64_e32 v[20:21], 0
	v_mov_b64_e32 v[22:23], 0
	v_mov_b64_e32 v[32:33], 0
	v_mov_b64_e32 v[34:35], 0
	v_mov_b64_e32 v[36:37], 0
	v_mov_b64_e32 v[38:39], 0
	v_mov_b64_e32 v[48:49], 0
	v_mov_b64_e32 v[50:51], 0
	v_mov_b64_e32 v[52:53], 0
	v_mov_b64_e32 v[54:55], 0
	v_mov_b64_e32 v[8:9], 0
	v_mov_b64_e32 v[10:11], 0
	v_mov_b64_e32 v[12:13], 0
	v_mov_b64_e32 v[14:15], 0
	v_mov_b64_e32 v[24:25], 0
	v_mov_b64_e32 v[26:27], 0
	v_mov_b64_e32 v[28:29], 0
	v_mov_b64_e32 v[30:31], 0
	v_mov_b64_e32 v[40:41], 0
	v_mov_b64_e32 v[42:43], 0
	v_mov_b64_e32 v[44:45], 0
	v_mov_b64_e32 v[46:47], 0
	v_mov_b64_e32 v[56:57], 0
	v_mov_b64_e32 v[58:59], 0
	v_mov_b64_e32 v[60:61], 0
	v_mov_b64_e32 v[62:63], 0
	v_mov_b64_e32 v[64:65], 0
	v_mov_b64_e32 v[66:67], 0
	v_mov_b64_e32 v[68:69], 0
	v_mov_b64_e32 v[70:71], 0
	v_mov_b64_e32 v[80:81], 0
	v_mov_b64_e32 v[82:83], 0
	v_mov_b64_e32 v[84:85], 0
	v_mov_b64_e32 v[86:87], 0
	v_mov_b64_e32 v[96:97], 0
	v_mov_b64_e32 v[98:99], 0
	v_mov_b64_e32 v[100:101], 0
	v_mov_b64_e32 v[102:103], 0
	v_mov_b64_e32 v[112:113], 0
	v_mov_b64_e32 v[114:115], 0
	v_mov_b64_e32 v[116:117], 0
	v_mov_b64_e32 v[118:119], 0
	v_mov_b64_e32 v[72:73], 0
	v_mov_b64_e32 v[74:75], 0
	v_mov_b64_e32 v[76:77], 0
	v_mov_b64_e32 v[78:79], 0
	v_mov_b64_e32 v[88:89], 0
	v_mov_b64_e32 v[90:91], 0
	v_mov_b64_e32 v[92:93], 0
	v_mov_b64_e32 v[94:95], 0
	v_mov_b64_e32 v[104:105], 0
	v_mov_b64_e32 v[106:107], 0
	v_mov_b64_e32 v[108:109], 0
	v_mov_b64_e32 v[110:111], 0
	v_mov_b64_e32 v[120:121], 0
	v_mov_b64_e32 v[122:123], 0
	v_mov_b64_e32 v[124:125], 0
	v_mov_b64_e32 v[126:127], 0

; template <class Epi, class Sched, bool ALIGN_EPI = false, bool SP2 = false>
; __device__ __forceinline__ void gemm_phase(PG8_LAS unsigned char* lds, const Gemm g, const Sched& S, const Epi& E) {
;     ...
;         const bool has_next = S.next(ui + 1, nxt);
;         const char* nA = has_next ? (const char*)g.A + (size_t)nxt.pm * tstep : cA; const char* nB = has_next ? (const char*)g.Bt + (size_t)nxt.pn * tstep : cB;
;     ...
;         for (int a = 0; a < 2; ++a)
; #pragma unroll
;             for (int b = 0; b < 2; ++b)
; #pragma unroll
;                 for (int m = 0; m < 4; ++m)
; #pragma unroll
;                     for (int n = 0; n < 2; ++n) acc[a][b][m][n] = (f32x4){0.f, 0.f, 0.f, 0.f};
.LBB0_1700:
	s_ashr_i32 s49, s48, 31
	s_lshl_b64 s[10:11], s[48:49], 20
	v_readlane_b32 s0, v244, 38
	s_add_u32 s40, s0, s10
	v_readlane_b32 s0, v244, 22
	s_addc_u32 s41, s0, s11
	s_and_b64 s[10:11], s[4:5], exec
	s_cselect_b32 s7, s41, s75
	s_cselect_b32 s12, s40, s74
	s_ashr_i32 s35, s34, 31
	s_lshl_b64 s[10:11], s[34:35], 20
	s_add_u32 s2, s92, s10
	s_addc_u32 s3, s51, s11
	s_and_b64 s[10:11], s[4:5], exec
	s_cselect_b32 s13, s3, s77
	s_cselect_b32 s16, s2, s76
	s_add_u32 s0, s74, 0x80080
	s_addc_u32 s1, s75, 0
	s_add_u32 s37, s76, 0x100
	v_mov_b64_e32 v[0:1], 0
	s_addc_u32 s71, s77, 0
	s_mov_b32 s73, -2
	v_mov_b64_e32 v[2:3], 0
	v_mov_b64_e32 v[16:17], 0
	v_mov_b64_e32 v[18:19], 0
	v_mov_b64_e32 v[4:5], 0
	v_mov_b64_e32 v[6:7], 0
	v_mov_b64_e32 v[20:21], 0
	v_mov_b64_e32 v[22:23], 0
	v_mov_b64_e32 v[8:9], 0
	v_mov_b64_e32 v[10:11], 0
	v_mov_b64_e32 v[24:25], 0
	v_mov_b64_e32 v[26:27], 0
	v_mov_b64_e32 v[12:13], 0
	v_mov_b64_e32 v[14:15], 0
	v_mov_b64_e32 v[28:29], 0
	v_mov_b64_e32 v[30:31], 0
	v_mov_b64_e32 v[32:33], 0
	v_mov_b64_e32 v[34:35], 0
	v_mov_b64_e32 v[48:49], 0
	v_mov_b64_e32 v[50:51], 0
	v_mov_b64_e32 v[36:37], 0
	v_mov_b64_e32 v[38:39], 0
	v_mov_b64_e32 v[52:53], 0
	v_mov_b64_e32 v[54:55], 0
	v_mov_b64_e32 v[40:41], 0
	v_mov_b64_e32 v[42:43], 0
	v_mov_b64_e32 v[56:57], 0
	v_mov_b64_e32 v[58:59], 0
	v_mov_b64_e32 v[44:45], 0
	v_mov_b64_e32 v[46:47], 0
	v_mov_b64_e32 v[60:61], 0
	v_mov_b64_e32 v[62:63], 0
	v_mov_b64_e32 v[64:65], 0
	v_mov_b64_e32 v[66:67], 0
	v_mov_b64_e32 v[84:85], 0
	v_mov_b64_e32 v[86:87], 0
	v_mov_b64_e32 v[68:69], 0
	v_mov_b64_e32 v[70:71], 0
	v_mov_b64_e32 v[88:89], 0
	v_mov_b64_e32 v[90:91], 0
	v_mov_b64_e32 v[72:73], 0
	v_mov_b64_e32 v[74:75], 0
	v_mov_b64_e32 v[96:97], 0
	v_mov_b64_e32 v[98:99], 0
	v_mov_b64_e32 v[76:77], 0
	v_mov_b64_e32 v[78:79], 0
	v_mov_b64_e32 v[100:101], 0
	v_mov_b64_e32 v[102:103], 0
	v_mov_b64_e32 v[92:93], 0
	v_mov_b64_e32 v[94:95], 0
	v_mov_b64_e32 v[80:81], 0
	v_mov_b64_e32 v[82:83], 0
	v_mov_b64_e32 v[108:109], 0
	v_mov_b64_e32 v[110:111], 0
	v_mov_b64_e32 v[104:105], 0
	v_mov_b64_e32 v[106:107], 0
	v_mov_b64_e32 v[112:113], 0
	v_mov_b64_e32 v[114:115], 0
	v_mov_b64_e32 v[120:121], 0
	v_mov_b64_e32 v[122:123], 0
	v_mov_b64_e32 v[116:117], 0
	v_mov_b64_e32 v[118:119], 0
	v_mov_b64_e32 v[124:125], 0
	v_mov_b64_e32 v[126:127], 0

; template <class Epi, class Sched, bool ALIGN_EPI = false, bool SP2 = false>
; __device__ __forceinline__ void gemm_phase(PG8_LAS unsigned char* lds, const Gemm g, const Sched& S, const Epi& E) {
;     ...
;         for (int a = 0; a < 2; ++a)
; #pragma unroll
;             for (int b = 0; b < 2; ++b)
; #pragma unroll
;                 for (int m = 0; m < 4; ++m)
; #pragma unroll
;                     for (int n = 0; n < 2; ++n) acc[a][b][m][n] = (f32x4){0.f, 0.f, 0.f, 0.f};
.LBB0_1923:
	s_add_u32 s22, s22, 0x160080
	s_addc_u32 s23, s23, 0
	s_add_u32 s61, s36, 0x100
	v_mov_b64_e32 v[0:1], 0
	s_addc_u32 s62, s37, 0
	s_mov_b32 s63, -2
	s_waitcnt lgkmcnt(0)
	v_mov_b64_e32 v[2:3], 0
	v_mov_b64_e32 v[4:5], 0
	v_mov_b64_e32 v[6:7], 0
	v_mov_b64_e32 v[16:17], 0
	v_mov_b64_e32 v[18:19], 0
	v_mov_b64_e32 v[20:21], 0
	v_mov_b64_e32 v[22:23], 0
	v_mov_b64_e32 v[32:33], 0
	v_mov_b64_e32 v[34:35], 0
	v_mov_b64_e32 v[36:37], 0
	v_mov_b64_e32 v[38:39], 0
	v_mov_b64_e32 v[48:49], 0
	v_mov_b64_e32 v[50:51], 0
	v_mov_b64_e32 v[52:53], 0
	v_mov_b64_e32 v[54:55], 0
	v_mov_b64_e32 v[8:9], 0
	v_mov_b64_e32 v[10:11], 0
	v_mov_b64_e32 v[12:13], 0
	v_mov_b64_e32 v[14:15], 0
	v_mov_b64_e32 v[24:25], 0
	v_mov_b64_e32 v[26:27], 0
	v_mov_b64_e32 v[28:29], 0
	v_mov_b64_e32 v[30:31], 0
	v_mov_b64_e32 v[40:41], 0
	v_mov_b64_e32 v[42:43], 0
	v_mov_b64_e32 v[44:45], 0
	v_mov_b64_e32 v[46:47], 0
	v_mov_b64_e32 v[56:57], 0
	v_mov_b64_e32 v[58:59], 0
	v_mov_b64_e32 v[60:61], 0
	v_mov_b64_e32 v[62:63], 0
	v_mov_b64_e32 v[64:65], 0
	v_mov_b64_e32 v[66:67], 0
	v_mov_b64_e32 v[68:69], 0
	v_mov_b64_e32 v[70:71], 0
	v_mov_b64_e32 v[80:81], 0
	v_mov_b64_e32 v[82:83], 0
	v_mov_b64_e32 v[84:85], 0
	v_mov_b64_e32 v[86:87], 0
	v_mov_b64_e32 v[96:97], 0
	v_mov_b64_e32 v[98:99], 0
	v_mov_b64_e32 v[100:101], 0
	v_mov_b64_e32 v[102:103], 0
	v_mov_b64_e32 v[112:113], 0
	v_mov_b64_e32 v[114:115], 0
	v_mov_b64_e32 v[116:117], 0
	v_mov_b64_e32 v[118:119], 0
	v_mov_b64_e32 v[72:73], 0
	v_mov_b64_e32 v[74:75], 0
	v_mov_b64_e32 v[76:77], 0
	v_mov_b64_e32 v[78:79], 0
	v_mov_b64_e32 v[88:89], 0
	v_mov_b64_e32 v[90:91], 0
	v_mov_b64_e32 v[92:93], 0
	v_mov_b64_e32 v[94:95], 0
	v_mov_b64_e32 v[104:105], 0
	v_mov_b64_e32 v[106:107], 0
	v_mov_b64_e32 v[108:109], 0
	v_mov_b64_e32 v[110:111], 0
	v_mov_b64_e32 v[120:121], 0
	v_mov_b64_e32 v[122:123], 0
	v_mov_b64_e32 v[124:125], 0
	v_mov_b64_e32 v[126:127], 0
